# v27 plus back-edge edit: one conditional backward branch per tile instead of cbranch plus s_branch in both attention loops
# speedup vs baseline: 1.0017x; 1.0017x over previous
; #define MFMA(a, b, c) __builtin_amdgcn_mfma_f32_32x32x16_bf16((a), (b), (c), 0, 0, 0)
; template <int DQK, bool ALIBI>
; DI void attn_pass(const u16* __restrict__ Qp, int ldq, const u16* __restrict__ Kp, int ldk, const u16* __restrict__ VTp,
;                   int seq_start, int kt_lo, int kt_hi, int q0, float slope2, f32x16 (&O)[4], float& lsum, char* lds) {
;     ...
; #pragma unroll
;     for (int s = 0; s < 2; ++s)
; #pragma unroll
;       for (int db = 0; db < 4; ++db) O[db] = MFMA(vg[s][db], pg[s], O[db]);
;     __syncthreads();
.Lmy_dif_g2:
	s_add_i32 s87, s87, 1
	s_add_i32 s6, s73, s87
	v_lshl_add_u64 v[138:139], v[138:139], 0, s[80:81]
	v_lshl_add_u64 v[140:141], v[140:141], 0, s[80:81]
	s_cmp_lt_i32 s6, s77
	v_mfma_f32_32x32x16_bf16 v[18:33], v[90:93], v[66:69], v[18:33]
	v_mfma_f32_32x32x16_bf16 v[2:17], v[94:97], v[66:69], v[2:17]
	v_mfma_f32_32x32x16_bf16 v[50:65], v[160:163], v[70:73], v[50:65]
	s_waitcnt lgkmcnt(0)
	s_barrier
	v_mfma_f32_32x32x16_bf16 v[34:49], v[164:167], v[70:73], v[34:49]
	v_mfma_f32_32x32x16_bf16 v[18:33], v[168:171], v[70:73], v[18:33]
	v_mfma_f32_32x32x16_bf16 v[2:17], v[82:85], v[70:73], v[2:17]
	s_mov_b32 s89, s88
	s_cbranch_scc1 .LBB0_1149
	s_branch .LBB0_1163

; #define MFMA(a, b, c) __builtin_amdgcn_mfma_f32_32x32x16_bf16((a), (b), (c), 0, 0, 0)
; template <int DQK, bool ALIBI>
; DI void attn_pass(const u16* __restrict__ Qp, int ldq, const u16* __restrict__ Kp, int ldk, const u16* __restrict__ VTp,
;                   int seq_start, int kt_lo, int kt_hi, int q0, float slope2, f32x16 (&O)[4], float& lsum, char* lds) {
;     ...
; #pragma unroll
;     for (int s = 0; s < 2; ++s)
; #pragma unroll
;       for (int db = 0; db < 4; ++db) O[db] = MFMA(vg[s][db], pg[s], O[db]);
;     __syncthreads();
.Lmy_mla_pv1:
	s_waitcnt lgkmcnt(4)
	v_mfma_f32_32x32x16_bf16 v[50:65], v[162:165], v[66:69], v[50:65]
	s_add_i32 s49, s49, 1
	s_add_i32 s44, s48, s49
	s_add_i32 s68, s68, 64
	v_lshl_add_u64 v[144:145], v[144:145], 0, s[80:81]
	v_lshl_add_u64 v[146:147], v[146:147], 0, s[80:81]
	s_cmp_lg_u32 s44, 2
	s_waitcnt lgkmcnt(3)
	v_mfma_f32_32x32x16_bf16 v[34:49], v[86:89], v[66:69], v[34:49]
	v_mfma_f32_32x32x16_bf16 v[18:33], v[90:93], v[66:69], v[18:33]
	v_mfma_f32_32x32x16_bf16 v[2:17], v[94:97], v[66:69], v[2:17]
	v_mfma_f32_32x32x16_bf16 v[50:65], v[166:169], v[70:73], v[50:65]
	s_waitcnt lgkmcnt(0)
	s_barrier
	v_mfma_f32_32x32x16_bf16 v[34:49], v[170:173], v[70:73], v[34:49]
	v_mfma_f32_32x32x16_bf16 v[18:33], v[174:177], v[70:73], v[18:33]
	v_mfma_f32_32x32x16_bf16 v[2:17], v[82:85], v[70:73], v[2:17]
	s_cbranch_scc1 .LBB0_1193
	s_branch .LBB0_1170
